# gMLP units rebalanced against the context attention units (8 vs 10 per workgroup)
# speedup vs baseline: 1.0138x; 1.0031x over previous
.LBB0_360:
	s_ashr_i32 s2, s14, 2
	s_and_b32 s18, s14, 3
	s_ashr_i32 s3, s2, 31
	s_lshl_b64 s[2:3], s[2:3], 7
	s_lshl_b32 s4, s18, 15
	s_add_u32 s4, s12, s4
	s_addc_u32 s5, s13, 0
	v_lshl_add_u64 v[0:1], v[22:23], 1, s[4:5]
	v_lshl_add_u64 v[0:1], v[0:1], 0, v[192:193]
	s_waitcnt lgkmcnt(0)
	s_barrier
	global_load_dwordx4 v[120:123], v[0:1], off
	s_lshl_b32 s44, s18, 8
	v_add_u32_e32 v4, v66, v65
	s_lshl_b32 s15, s18, 7
	v_add_u32_e32 v44, s15, v16
	v_ashrrev_i32_e32 v45, 31, v44
	v_lshl_add_u64 v[44:45], v[44:45], 2, s[6:7]
	v_lshl_add_u64 v[56:57], s[2:3], 0, v[16:17]
	v_lshlrev_b32_e32 v46, 1, v18
	v_mov_b32_e32 v47, v193
	v_add_u32_e32 v8, v29, v41
	v_add_u32_e32 v12, v29, v43
	v_or_b32_e32 v103, s15, v18
	s_cmpk_lg_i32 s82, 0x100
	s_cbranch_scc1 .Lgm_plain
	s_add_i32 s98, s14, s82
	s_cmpk_lt_i32 s98, 0x800
	s_cbranch_scc1 .Lgm_set
	s_cmpk_lt_i32 s14, 0x800
	s_cbranch_scc0 .Lgm_tail
	s_and_b32 s99, s14, 0xff
	s_movk_i32 s98, 0x900
	s_cmpk_lt_i32 s99, 0x80
	s_cbranch_scc1 .Lgm_set
	s_lshl_b32 s99, s99, 1
	s_add_i32 s98, s99, 0x700
	s_branch .Lgm_set
.Lgm_tail:
	s_movk_i32 s98, 0x900
	s_bitcmp1_b32 s14, 0
	s_cbranch_scc1 .Lgm_set
	s_add_i32 s98, s14, 1
	s_branch .Lgm_set
.Lgm_plain:
	s_add_i32 s98, s14, s82
.Lgm_set:
	s_mov_b32 s14, s98
	s_cmpk_lt_i32 s14, 0x900
	v_lshl_add_u64 v[152:153], s[2:3], 0, v[20:21]
	v_lshlrev_b64 v[152:153], 12, v[152:153]
	v_lshl_add_u64 v[152:153], s[0:1], 0, v[152:153]
	v_lshl_add_u64 v[152:153], v[152:153], 0, s[44:45]
	v_lshl_add_u64 v[152:153], v[152:153], 0, v[192:193]
	global_load_dwordx4 v[124:127], v[152:153], off offset:1024
	v_lshl_add_u64 v[152:153], v[26:27], 1, s[4:5]
	v_lshl_add_u64 v[152:153], v[152:153], 0, v[192:193]
	global_load_dwordx4 v[128:131], v[152:153], off
	v_lshl_add_u64 v[152:153], s[2:3], 0, v[24:25]
	v_lshlrev_b64 v[152:153], 12, v[152:153]
	v_lshl_add_u64 v[152:153], s[0:1], 0, v[152:153]
	v_lshl_add_u64 v[152:153], v[152:153], 0, s[44:45]
	v_lshl_add_u64 v[152:153], v[152:153], 0, v[192:193]
	global_load_dwordx4 v[132:135], v[152:153], off offset:1024
	v_lshl_add_u64 v[152:153], v[32:33], 1, s[4:5]
	v_lshl_add_u64 v[152:153], v[152:153], 0, v[192:193]
	global_load_dwordx4 v[136:139], v[152:153], off
	v_lshl_add_u64 v[152:153], s[2:3], 0, v[30:31]
	v_lshlrev_b64 v[152:153], 12, v[152:153]
	v_lshl_add_u64 v[152:153], s[0:1], 0, v[152:153]
	v_lshl_add_u64 v[152:153], v[152:153], 0, s[44:45]
	v_lshl_add_u64 v[152:153], v[152:153], 0, v[192:193]
	global_load_dwordx4 v[140:143], v[152:153], off offset:1024
	v_lshl_add_u64 v[152:153], v[38:39], 1, s[4:5]
	v_lshl_add_u64 v[152:153], v[152:153], 0, v[192:193]
	global_load_dwordx4 v[144:147], v[152:153], off
	v_lshl_add_u64 v[152:153], s[2:3], 0, v[36:37]
	v_lshlrev_b64 v[152:153], 12, v[152:153]
	v_lshl_add_u64 v[152:153], s[0:1], 0, v[152:153]
	v_lshl_add_u64 v[152:153], v[152:153], 0, s[44:45]
	v_lshl_add_u64 v[152:153], v[152:153], 0, v[192:193]
	global_load_dwordx4 v[148:151], v[152:153], off offset:1024
	s_waitcnt vmcnt(7)
	ds_write_b128 v67, v[120:123]
	s_waitcnt vmcnt(6)
	ds_write_b16 v4, v124 offset:32768
	ds_write_b16_d16_hi v68, v124 offset:33024
	ds_write_b16 v69, v125 offset:33280
	ds_write_b16_d16_hi v70, v125 offset:33536
	ds_write_b16 v71, v126 offset:33792
	ds_write_b16_d16_hi v72, v126 offset:34048
	ds_write_b16 v73, v127 offset:34304
	ds_write_b16_d16_hi v74, v127 offset:34560
	v_add_u32_e32 v4, v28, v64
	s_waitcnt vmcnt(5)
	ds_write_b128 v4, v[128:131]
	s_waitcnt vmcnt(4)
	ds_write_b16 v75, v132 offset:32768
	ds_write_b16_d16_hi v76, v132 offset:33024
	ds_write_b16 v77, v133 offset:33280
	ds_write_b16_d16_hi v78, v133 offset:33536
	ds_write_b16 v79, v134 offset:33792
	ds_write_b16_d16_hi v80, v134 offset:34048
	ds_write_b16 v81, v135 offset:34304
	ds_write_b16_d16_hi v82, v135 offset:34560
	v_add_u32_e32 v4, v34, v64
	s_waitcnt vmcnt(3)
	ds_write_b128 v4, v[136:139]
	s_waitcnt vmcnt(2)
	ds_write_b16 v83, v140 offset:32768
	ds_write_b16_d16_hi v84, v140 offset:33024
	ds_write_b16 v85, v141 offset:33280
	ds_write_b16_d16_hi v86, v141 offset:33536
	ds_write_b16 v87, v142 offset:33792
	ds_write_b16_d16_hi v88, v142 offset:34048
	ds_write_b16 v89, v143 offset:34304
	ds_write_b16_d16_hi v90, v143 offset:34560
	v_add_u32_e32 v4, v40, v64
	s_waitcnt vmcnt(1)
	ds_write_b128 v4, v[144:147]
	s_waitcnt vmcnt(0)
	ds_write_b16 v91, v148 offset:32768
	ds_write_b16_d16_hi v92, v148 offset:33024
	ds_write_b16 v93, v149 offset:33280
	ds_write_b16_d16_hi v94, v149 offset:33536
	ds_write_b16 v95, v150 offset:33792
	ds_write_b16_d16_hi v96, v150 offset:34048
	ds_write_b16 v97, v151 offset:34304
	ds_write_b16_d16_hi v98, v151 offset:34560
	v_add_u32_e32 v4, v29, v35
	s_waitcnt lgkmcnt(0)
	s_barrier
	global_load_dword v42, v[44:45], off
	v_lshlrev_b64 v[44:45], 12, v[56:57]
	v_lshl_add_u64 v[44:45], s[0:1], 0, v[44:45]
	v_lshl_add_u64 v[44:45], v[44:45], 0, s[44:45]
	v_add_u32_e32 v0, v29, v19
	v_lshl_add_u64 v[44:45], v[44:45], 0, v[46:47]
	ds_read_b128 v[0:3], v0
	ds_read_b128 v[4:7], v4
	ds_read_b128 v[8:11], v8
	ds_read_b128 v[12:15], v12
	global_load_dwordx2 v[108:109], v[44:45], off
	global_load_dwordx2 v[58:59], v[44:45], off offset:32
	global_load_dwordx2 v[54:55], v[44:45], off offset:64
	global_load_dwordx2 v[52:53], v[44:45], off offset:96
	global_load_dwordx2 v[50:51], v[44:45], off offset:128
	global_load_dwordx2 v[48:49], v[44:45], off offset:160
	global_load_dwordx2 v[46:47], v[44:45], off offset:192
	s_nop 0
	global_load_dwordx2 v[44:45], v[44:45], off offset:224
	ds_read_b128 v[60:63], v99 offset:32768
	ds_read_b128 v[104:107], v100 offset:32768
	s_waitcnt lgkmcnt(1)
	v_mfma_f32_16x16x32_bf16 v[60:63], v[60:63], v[0:3], 0
	v_lshlrev_b64 v[56:57], 11, v[56:57]
	v_lshl_add_u64 v[56:57], s[10:11], 0, v[56:57]
	s_waitcnt lgkmcnt(0)
	v_mfma_f32_16x16x32_bf16 v[60:63], v[104:107], v[4:7], v[60:63]
	ds_read_b128 v[104:107], v101 offset:32768
	s_waitcnt lgkmcnt(0)
	v_mfma_f32_16x16x32_bf16 v[60:63], v[104:107], v[8:11], v[60:63]
	ds_read_b128 v[104:107], v102 offset:32768
	s_waitcnt lgkmcnt(0)
	v_mfma_f32_16x16x32_bf16 v[60:63], v[104:107], v[12:15], v[60:63]
	s_waitcnt vmcnt(7)
	v_lshlrev_b32_e32 v104, 16, v108
	v_and_b32_e32 v105, 0xffff0000, v108
	v_pk_mul_f32 v[106:107], v[104:105], s[20:21] op_sel_hi:[1,0]
	s_nop 3
	v_pk_add_f32 v[60:61], v[42:43], v[60:61] op_sel_hi:[0,1]
	v_pk_mul_f32 v[106:107], v[106:107], v[104:105]
	v_pk_add_f32 v[62:63], v[42:43], v[62:63] op_sel_hi:[0,1]
	v_pk_fma_f32 v[106:107], v[106:107], v[104:105], v[104:105]
	v_pk_mul_f32 v[104:105], v[104:105], 0.5 op_sel_hi:[1,0]
	v_pk_mul_f32 v[106:107], v[106:107], s[22:23] op_sel_hi:[1,0]
	s_nop 0
	v_mul_f32_e64 v108, |v106|, -2.0
	v_mul_f32_e32 v108, 0x3fb8aa3b, v108
	v_exp_f32_e32 v110, v108
	v_cmp_gt_f32_e32 vcc, 0, v106
	v_cmp_gt_f32_e64 s[4:5], 0, v107
	v_add_f32_e32 v108, 1.0, v110
	v_rcp_f32_e32 v112, v108
	v_mul_f32_e64 v108, |v107|, -2.0
	v_mul_f32_e32 v108, 0x3fb8aa3b, v108
	v_exp_f32_e32 v111, v108
	s_nop 0
	v_add_f32_e32 v108, 1.0, v111
	v_rcp_f32_e32 v113, v108
	v_pk_add_f32 v[114:115], v[110:111], 1.0 op_sel_hi:[1,0] neg_lo:[1,0] neg_hi:[1,0]
	s_nop 0
	v_pk_mul_f32 v[110:111], v[114:115], v[112:113]
	s_nop 0
	v_cndmask_b32_e64 v107, v111, -v111, s[4:5]
	v_cndmask_b32_e64 v106, v110, -v110, vcc
	v_pk_add_f32 v[106:107], v[106:107], 1.0 op_sel_hi:[1,0]
	s_nop 0
	v_pk_mul_f32 v[104:105], v[104:105], v[106:107]
	s_nop 0
	v_pk_mul_f32 v[60:61], v[60:61], v[104:105]
	v_lshlrev_b32_e32 v104, 16, v109
	v_and_b32_e32 v105, 0xffff0000, v109
	v_pk_mul_f32 v[106:107], v[104:105], s[20:21] op_sel_hi:[1,0]
	v_cvt_pk_bf16_f32 v60, v60, v61
	v_pk_mul_f32 v[106:107], v[106:107], v[104:105]
	s_nop 0
	v_pk_fma_f32 v[106:107], v[106:107], v[104:105], v[104:105]
	v_pk_mul_f32 v[104:105], v[104:105], 0.5 op_sel_hi:[1,0]
	v_pk_mul_f32 v[106:107], v[106:107], s[22:23] op_sel_hi:[1,0]
	s_nop 0
	v_mul_f32_e64 v108, |v106|, -2.0
	v_mul_f32_e32 v108, 0x3fb8aa3b, v108
	v_exp_f32_e32 v108, v108
	v_cmp_gt_f32_e32 vcc, 0, v106
	v_cmp_gt_f32_e64 s[4:5], 0, v107
	v_add_f32_e32 v109, 1.0, v108
	v_rcp_f32_e32 v110, v109
	v_mul_f32_e64 v109, |v107|, -2.0
	v_mul_f32_e32 v109, 0x3fb8aa3b, v109
	v_exp_f32_e32 v109, v109
	s_nop 0
	v_pk_add_f32 v[112:113], v[108:109], 1.0 op_sel_hi:[1,0] neg_lo:[1,0] neg_hi:[1,0]
	v_add_f32_e32 v108, 1.0, v109
	v_rcp_f32_e32 v111, v108
	s_nop 0
	v_pk_mul_f32 v[108:109], v[112:113], v[110:111]
	s_nop 0
	v_cndmask_b32_e64 v107, v109, -v109, s[4:5]
	v_cndmask_b32_e64 v106, v108, -v108, vcc
	v_pk_add_f32 v[106:107], v[106:107], 1.0 op_sel_hi:[1,0]
	s_nop 0
	v_pk_mul_f32 v[104:105], v[104:105], v[106:107]
	s_nop 0
	v_pk_mul_f32 v[62:63], v[62:63], v[104:105]
	ds_read_b128 v[104:107], v157 offset:36864
	v_cvt_pk_bf16_f32 v61, v62, v63
	v_lshlrev_b32_e32 v62, 1, v103
	v_mov_b32_e32 v63, v193
	v_lshl_add_u64 v[56:57], v[56:57], 0, v[62:63]
	global_store_dwordx2 v[56:57], v[60:61], off
	ds_read_b128 v[60:63], v156 offset:36864
	s_waitcnt lgkmcnt(0)
	v_mfma_f32_16x16x32_bf16 v[60:63], v[60:63], v[0:3], 0
	v_mfma_f32_16x16x32_bf16 v[60:63], v[104:107], v[4:7], v[60:63]
	ds_read_b128 v[104:107], v158 offset:36864
	s_waitcnt lgkmcnt(0)
	v_mfma_f32_16x16x32_bf16 v[60:63], v[104:107], v[8:11], v[60:63]
	ds_read_b128 v[104:107], v159 offset:36864
	s_waitcnt lgkmcnt(0)
	v_mfma_f32_16x16x32_bf16 v[60:63], v[104:107], v[12:15], v[60:63]
	s_waitcnt vmcnt(7)
	v_lshlrev_b32_e32 v104, 16, v58
	v_and_b32_e32 v105, 0xffff0000, v58
	v_pk_mul_f32 v[106:107], v[104:105], s[20:21] op_sel_hi:[1,0]
	s_nop 3
	v_pk_add_f32 v[60:61], v[42:43], v[60:61] op_sel_hi:[0,1]
	v_pk_mul_f32 v[106:107], v[106:107], v[104:105]
	v_pk_add_f32 v[62:63], v[42:43], v[62:63] op_sel_hi:[0,1]
	v_pk_fma_f32 v[106:107], v[106:107], v[104:105], v[104:105]
	v_pk_mul_f32 v[104:105], v[104:105], 0.5 op_sel_hi:[1,0]
	v_pk_mul_f32 v[106:107], v[106:107], s[22:23] op_sel_hi:[1,0]
	s_nop 0
	v_mul_f32_e64 v58, |v106|, -2.0
	v_mul_f32_e32 v58, 0x3fb8aa3b, v58
	v_exp_f32_e32 v108, v58
	v_cmp_gt_f32_e32 vcc, 0, v106
	v_cmp_gt_f32_e64 s[4:5], 0, v107
	v_add_f32_e32 v58, 1.0, v108
	v_rcp_f32_e32 v110, v58
	v_mul_f32_e64 v58, |v107|, -2.0
	v_mul_f32_e32 v58, 0x3fb8aa3b, v58
	v_exp_f32_e32 v109, v58
	s_nop 0
	v_add_f32_e32 v58, 1.0, v109
	v_rcp_f32_e32 v111, v58
	v_pk_add_f32 v[112:113], v[108:109], 1.0 op_sel_hi:[1,0] neg_lo:[1,0] neg_hi:[1,0]
	v_lshlrev_b32_e32 v58, 16, v59
	v_and_b32_e32 v59, 0xffff0000, v59
	v_pk_mul_f32 v[108:109], v[112:113], v[110:111]
	s_nop 0
	v_cndmask_b32_e64 v107, v109, -v109, s[4:5]
	v_cndmask_b32_e64 v106, v108, -v108, vcc
	v_pk_add_f32 v[106:107], v[106:107], 1.0 op_sel_hi:[1,0]
	s_nop 0
	v_pk_mul_f32 v[104:105], v[104:105], v[106:107]
	s_nop 0
	v_pk_mul_f32 v[60:61], v[104:105], v[60:61]
	v_pk_mul_f32 v[104:105], v[58:59], s[20:21] op_sel_hi:[1,0]
	v_cvt_pk_bf16_f32 v60, v60, v61
	v_pk_mul_f32 v[104:105], v[104:105], v[58:59]
	s_nop 0
	v_pk_fma_f32 v[104:105], v[104:105], v[58:59], v[58:59]
	v_pk_mul_f32 v[58:59], v[58:59], 0.5 op_sel_hi:[1,0]
	v_pk_mul_f32 v[104:105], v[104:105], s[22:23] op_sel_hi:[1,0]
	s_nop 0
	v_mul_f32_e64 v103, |v104|, -2.0
	v_mul_f32_e32 v103, 0x3fb8aa3b, v103
	v_exp_f32_e32 v106, v103
	v_cmp_gt_f32_e32 vcc, 0, v104
	v_cmp_gt_f32_e64 s[4:5], 0, v105
	v_add_f32_e32 v103, 1.0, v106
	v_rcp_f32_e32 v108, v103
	v_mul_f32_e64 v103, |v105|, -2.0
	v_mul_f32_e32 v103, 0x3fb8aa3b, v103
	v_exp_f32_e32 v107, v103
	s_nop 0
	v_add_f32_e32 v103, 1.0, v107
	v_rcp_f32_e32 v109, v103
	v_pk_add_f32 v[110:111], v[106:107], 1.0 op_sel_hi:[1,0] neg_lo:[1,0] neg_hi:[1,0]
	s_nop 0
	v_pk_mul_f32 v[106:107], v[110:111], v[108:109]
	s_nop 0
	v_cndmask_b32_e64 v105, v107, -v107, s[4:5]
	v_cndmask_b32_e64 v104, v106, -v106, vcc
	v_pk_add_f32 v[104:105], v[104:105], 1.0 op_sel_hi:[1,0]
	s_nop 0
	v_pk_mul_f32 v[58:59], v[58:59], v[104:105]
	ds_read_b128 v[104:107], v161 offset:40960
	v_pk_mul_f32 v[58:59], v[58:59], v[62:63]
	s_waitcnt vmcnt(6)
	v_lshlrev_b32_e32 v62, 16, v54
	v_cvt_pk_bf16_f32 v61, v58, v59
	global_store_dwordx2 v[56:57], v[60:61], off offset:32
	ds_read_b128 v[58:61], v160 offset:40960
	s_waitcnt lgkmcnt(0)
	v_mfma_f32_16x16x32_bf16 v[58:61], v[58:61], v[0:3], 0
	v_and_b32_e32 v63, 0xffff0000, v54
	v_mfma_f32_16x16x32_bf16 v[58:61], v[104:107], v[4:7], v[58:61]
	ds_read_b128 v[104:107], v162 offset:40960
	s_waitcnt lgkmcnt(0)
	v_mfma_f32_16x16x32_bf16 v[58:61], v[104:107], v[8:11], v[58:61]
	ds_read_b128 v[104:107], v163 offset:40960
	s_waitcnt lgkmcnt(0)
	v_mfma_f32_16x16x32_bf16 v[58:61], v[104:107], v[12:15], v[58:61]
	v_mul_f32_e64 v104, v62, s20
	v_mul_f32_e64 v105, v63, s20
	s_nop 5
	v_pk_add_f32 v[58:59], v[42:43], v[58:59] op_sel_hi:[0,1]
	v_pk_mul_f32 v[104:105], v[104:105], v[62:63]
	v_pk_add_f32 v[60:61], v[42:43], v[60:61] op_sel_hi:[0,1]
	v_pk_fma_f32 v[104:105], v[104:105], v[62:63], v[62:63]
	v_pk_mul_f32 v[62:63], v[62:63], 0.5 op_sel_hi:[1,0]
	v_pk_mul_f32 v[104:105], v[104:105], s[22:23] op_sel_hi:[1,0]
	s_nop 0
	v_mul_f32_e64 v54, |v104|, -2.0
	v_mul_f32_e32 v54, 0x3fb8aa3b, v54
	v_exp_f32_e32 v106, v54
	v_cmp_gt_f32_e32 vcc, 0, v104
	v_cmp_gt_f32_e64 s[4:5], 0, v105
	v_add_f32_e32 v54, 1.0, v106
	v_rcp_f32_e32 v108, v54
	v_mul_f32_e64 v54, |v105|, -2.0
	v_mul_f32_e32 v54, 0x3fb8aa3b, v54
	v_exp_f32_e32 v107, v54
	s_nop 0
	v_add_f32_e32 v54, 1.0, v107
	v_rcp_f32_e32 v109, v54
	v_pk_add_f32 v[110:111], v[106:107], 1.0 op_sel_hi:[1,0] neg_lo:[1,0] neg_hi:[1,0]
	v_lshlrev_b32_e32 v54, 16, v55
	v_and_b32_e32 v55, 0xffff0000, v55
	v_pk_mul_f32 v[106:107], v[110:111], v[108:109]
	s_nop 0
	v_cndmask_b32_e64 v105, v107, -v107, s[4:5]
	v_cndmask_b32_e64 v104, v106, -v106, vcc
	v_pk_add_f32 v[104:105], v[104:105], 1.0 op_sel_hi:[1,0]
	s_nop 0
	v_pk_mul_f32 v[62:63], v[62:63], v[104:105]
	s_nop 0
	v_pk_mul_f32 v[58:59], v[62:63], v[58:59]
	v_pk_mul_f32 v[62:63], v[54:55], s[20:21] op_sel_hi:[1,0]
	v_cvt_pk_bf16_f32 v58, v58, v59
	v_pk_mul_f32 v[62:63], v[62:63], v[54:55]
	s_nop 0
	v_pk_fma_f32 v[62:63], v[62:63], v[54:55], v[54:55]
	v_pk_mul_f32 v[54:55], v[54:55], 0.5 op_sel_hi:[1,0]
	v_pk_mul_f32 v[62:63], v[62:63], s[22:23] op_sel_hi:[1,0]
	s_nop 0
	v_mul_f32_e64 v103, |v62|, -2.0
	v_mul_f32_e32 v103, 0x3fb8aa3b, v103
	v_exp_f32_e32 v104, v103
	v_cmp_gt_f32_e32 vcc, 0, v62
	v_cmp_gt_f32_e64 s[4:5], 0, v63
	v_add_f32_e32 v103, 1.0, v104
	v_rcp_f32_e32 v106, v103
	v_mul_f32_e64 v103, |v63|, -2.0
	v_mul_f32_e32 v103, 0x3fb8aa3b, v103
	v_exp_f32_e32 v105, v103
	s_nop 0
	v_add_f32_e32 v103, 1.0, v105
	v_rcp_f32_e32 v107, v103
	v_pk_add_f32 v[108:109], v[104:105], 1.0 op_sel_hi:[1,0] neg_lo:[1,0] neg_hi:[1,0]
	s_nop 0
	v_pk_mul_f32 v[104:105], v[108:109], v[106:107]
	s_nop 0
	v_cndmask_b32_e64 v63, v105, -v105, s[4:5]
	v_cndmask_b32_e64 v62, v104, -v104, vcc
	v_pk_add_f32 v[62:63], v[62:63], 1.0 op_sel_hi:[1,0]
	ds_read_b128 v[104:107], v165 offset:45056
	v_pk_mul_f32 v[54:55], v[54:55], v[62:63]
	s_nop 0
	v_pk_mul_f32 v[54:55], v[54:55], v[60:61]
	s_nop 0
	v_cvt_pk_bf16_f32 v59, v54, v55
	global_store_dwordx2 v[56:57], v[58:59], off offset:64
	ds_read_b128 v[58:61], v164 offset:45056
	s_waitcnt lgkmcnt(0)
	v_mfma_f32_16x16x32_bf16 v[58:61], v[58:61], v[0:3], 0
	s_waitcnt vmcnt(7)
	v_lshlrev_b32_e32 v54, 16, v52
	v_and_b32_e32 v55, 0xffff0000, v52
	v_pk_mul_f32 v[62:63], v[54:55], s[20:21] op_sel_hi:[1,0]
	v_mfma_f32_16x16x32_bf16 v[58:61], v[104:107], v[4:7], v[58:61]
	ds_read_b128 v[104:107], v166 offset:45056
	v_pk_mul_f32 v[62:63], v[62:63], v[54:55]
	s_waitcnt lgkmcnt(0)
	v_mfma_f32_16x16x32_bf16 v[58:61], v[104:107], v[8:11], v[58:61]
	ds_read_b128 v[104:107], v167 offset:45056
	v_pk_fma_f32 v[62:63], v[62:63], v[54:55], v[54:55]
	v_pk_mul_f32 v[54:55], v[54:55], 0.5 op_sel_hi:[1,0]
	v_pk_mul_f32 v[62:63], v[62:63], s[22:23] op_sel_hi:[1,0]
	s_waitcnt lgkmcnt(0)
	v_mfma_f32_16x16x32_bf16 v[58:61], v[104:107], v[12:15], v[58:61]
	v_mul_f32_e64 v52, |v62|, -2.0
	v_mul_f32_e32 v52, 0x3fb8aa3b, v52
	v_exp_f32_e32 v104, v52
	v_cmp_gt_f32_e32 vcc, 0, v62
	v_cmp_gt_f32_e64 s[4:5], 0, v63
	s_nop 2
	v_pk_add_f32 v[58:59], v[42:43], v[58:59] op_sel_hi:[0,1]
	v_add_f32_e32 v52, 1.0, v104
	v_rcp_f32_e32 v106, v52
	v_mul_f32_e64 v52, |v63|, -2.0
	v_mul_f32_e32 v52, 0x3fb8aa3b, v52
	v_exp_f32_e32 v105, v52
	s_nop 0
	v_add_f32_e32 v52, 1.0, v105
	v_rcp_f32_e32 v107, v52
	v_pk_add_f32 v[108:109], v[104:105], 1.0 op_sel_hi:[1,0] neg_lo:[1,0] neg_hi:[1,0]
	v_lshlrev_b32_e32 v52, 16, v53
	v_and_b32_e32 v53, 0xffff0000, v53
	v_pk_mul_f32 v[104:105], v[108:109], v[106:107]
	s_nop 0
	v_cndmask_b32_e64 v63, v105, -v105, s[4:5]
	v_cndmask_b32_e64 v62, v104, -v104, vcc
	v_pk_add_f32 v[62:63], v[62:63], 1.0 op_sel_hi:[1,0]
	s_nop 0
	v_pk_mul_f32 v[54:55], v[54:55], v[62:63]
	s_nop 0
	v_pk_mul_f32 v[54:55], v[54:55], v[58:59]
	v_pk_mul_f32 v[58:59], v[52:53], s[20:21] op_sel_hi:[1,0]
	v_cvt_pk_bf16_f32 v54, v54, v55
	v_pk_mul_f32 v[58:59], v[58:59], v[52:53]
	s_nop 0
	v_pk_fma_f32 v[58:59], v[58:59], v[52:53], v[52:53]
	v_pk_mul_f32 v[52:53], v[52:53], 0.5 op_sel_hi:[1,0]
	v_pk_mul_f32 v[58:59], v[58:59], s[22:23] op_sel_hi:[1,0]
	s_nop 0
	v_mul_f32_e64 v62, |v58|, -2.0
	v_mul_f32_e32 v62, 0x3fb8aa3b, v62
	v_exp_f32_e32 v62, v62
	v_cmp_gt_f32_e32 vcc, 0, v58
	v_cmp_gt_f32_e64 s[4:5], 0, v59
	v_add_f32_e32 v63, 1.0, v62
	v_rcp_f32_e32 v104, v63
	v_mul_f32_e64 v63, |v59|, -2.0
	v_mul_f32_e32 v63, 0x3fb8aa3b, v63
	v_exp_f32_e32 v63, v63
	s_nop 0
	v_pk_add_f32 v[106:107], v[62:63], 1.0 op_sel_hi:[1,0] neg_lo:[1,0] neg_hi:[1,0]
	v_add_f32_e32 v62, 1.0, v63
	v_rcp_f32_e32 v105, v62
	s_nop 0
	v_pk_mul_f32 v[62:63], v[106:107], v[104:105]
	s_nop 0
	v_cndmask_b32_e64 v59, v63, -v63, s[4:5]
	v_cndmask_b32_e64 v58, v62, -v62, vcc
	v_pk_add_f32 v[58:59], v[58:59], 1.0 op_sel_hi:[1,0]
	s_nop 0
	v_pk_mul_f32 v[52:53], v[52:53], v[58:59]
	v_pk_add_f32 v[58:59], v[42:43], v[60:61] op_sel_hi:[0,1]
	v_pk_mul_f32 v[52:53], v[52:53], v[58:59]
	ds_read_b128 v[58:61], v169 offset:49152
	v_cvt_pk_bf16_f32 v55, v52, v53
	global_store_dwordx2 v[56:57], v[54:55], off offset:96
	ds_read_b128 v[52:55], v168 offset:49152
	s_waitcnt lgkmcnt(0)
	v_mfma_f32_16x16x32_bf16 v[52:55], v[52:55], v[0:3], 0
	v_mfma_f32_16x16x32_bf16 v[52:55], v[58:61], v[4:7], v[52:55]
	ds_read_b128 v[58:61], v170 offset:49152
	s_waitcnt lgkmcnt(0)
	v_mfma_f32_16x16x32_bf16 v[52:55], v[58:61], v[8:11], v[52:55]
	ds_read_b128 v[58:61], v171 offset:49152
	s_waitcnt lgkmcnt(0)
	v_mfma_f32_16x16x32_bf16 v[52:55], v[58:61], v[12:15], v[52:55]
	s_waitcnt vmcnt(7)
	v_lshlrev_b32_e32 v58, 16, v50
	v_and_b32_e32 v59, 0xffff0000, v50
	v_pk_mul_f32 v[60:61], v[58:59], s[20:21] op_sel_hi:[1,0]
	s_nop 3
	v_pk_add_f32 v[52:53], v[42:43], v[52:53] op_sel_hi:[0,1]
	v_pk_mul_f32 v[60:61], v[60:61], v[58:59]
	v_pk_add_f32 v[54:55], v[42:43], v[54:55] op_sel_hi:[0,1]
	v_pk_fma_f32 v[60:61], v[60:61], v[58:59], v[58:59]
	v_pk_mul_f32 v[58:59], v[58:59], 0.5 op_sel_hi:[1,0]
	v_pk_mul_f32 v[60:61], v[60:61], s[22:23] op_sel_hi:[1,0]
	s_nop 0
	v_mul_f32_e64 v50, |v60|, -2.0
	v_mul_f32_e32 v50, 0x3fb8aa3b, v50
	v_exp_f32_e32 v62, v50
	v_cmp_gt_f32_e32 vcc, 0, v60
	v_cmp_gt_f32_e64 s[4:5], 0, v61
	v_add_f32_e32 v50, 1.0, v62
	v_rcp_f32_e32 v104, v50
	v_mul_f32_e64 v50, |v61|, -2.0
	v_mul_f32_e32 v50, 0x3fb8aa3b, v50
	v_exp_f32_e32 v63, v50
	s_nop 0
	v_add_f32_e32 v50, 1.0, v63
	v_rcp_f32_e32 v105, v50
	v_pk_add_f32 v[106:107], v[62:63], 1.0 op_sel_hi:[1,0] neg_lo:[1,0] neg_hi:[1,0]
	v_lshlrev_b32_e32 v50, 16, v51
	v_and_b32_e32 v51, 0xffff0000, v51
	v_pk_mul_f32 v[62:63], v[106:107], v[104:105]
	s_nop 0
	v_cndmask_b32_e64 v61, v63, -v63, s[4:5]
	v_cndmask_b32_e64 v60, v62, -v62, vcc
	v_pk_add_f32 v[60:61], v[60:61], 1.0 op_sel_hi:[1,0]
	s_nop 0
	v_pk_mul_f32 v[58:59], v[58:59], v[60:61]
	s_nop 0
	v_pk_mul_f32 v[52:53], v[58:59], v[52:53]
	v_pk_mul_f32 v[58:59], v[50:51], s[20:21] op_sel_hi:[1,0]
	v_cvt_pk_bf16_f32 v52, v52, v53
	v_pk_mul_f32 v[58:59], v[58:59], v[50:51]
	s_nop 0
	v_pk_fma_f32 v[58:59], v[58:59], v[50:51], v[50:51]
	v_pk_mul_f32 v[50:51], v[50:51], 0.5 op_sel_hi:[1,0]
	v_pk_mul_f32 v[58:59], v[58:59], s[22:23] op_sel_hi:[1,0]
	s_nop 0
	v_mul_f32_e64 v60, |v58|, -2.0
	v_mul_f32_e32 v60, 0x3fb8aa3b, v60
	v_exp_f32_e32 v60, v60
	v_cmp_gt_f32_e32 vcc, 0, v58
	v_cmp_gt_f32_e64 s[4:5], 0, v59
	v_add_f32_e32 v61, 1.0, v60
	v_rcp_f32_e32 v62, v61
	v_mul_f32_e64 v61, |v59|, -2.0
	v_mul_f32_e32 v61, 0x3fb8aa3b, v61
	v_exp_f32_e32 v61, v61
	s_nop 0
	v_pk_add_f32 v[104:105], v[60:61], 1.0 op_sel_hi:[1,0] neg_lo:[1,0] neg_hi:[1,0]
	v_add_f32_e32 v60, 1.0, v61
	v_rcp_f32_e32 v63, v60
	s_nop 0
	v_pk_mul_f32 v[60:61], v[104:105], v[62:63]
	s_nop 0
	v_cndmask_b32_e64 v59, v61, -v61, s[4:5]
	v_cndmask_b32_e64 v58, v60, -v60, vcc
	v_pk_add_f32 v[58:59], v[58:59], 1.0 op_sel_hi:[1,0]
	s_nop 0
	v_pk_mul_f32 v[50:51], v[50:51], v[58:59]
	ds_read_b128 v[58:61], v173 offset:53248
	v_pk_mul_f32 v[50:51], v[50:51], v[54:55]
	s_waitcnt vmcnt(6)
	v_lshlrev_b32_e32 v54, 16, v48
	v_cvt_pk_bf16_f32 v53, v50, v51
	global_store_dwordx2 v[56:57], v[52:53], off offset:128
	ds_read_b128 v[50:53], v172 offset:53248
	s_waitcnt lgkmcnt(0)
	v_mfma_f32_16x16x32_bf16 v[50:53], v[50:53], v[0:3], 0
	v_and_b32_e32 v55, 0xffff0000, v48
	v_mfma_f32_16x16x32_bf16 v[50:53], v[58:61], v[4:7], v[50:53]
	ds_read_b128 v[58:61], v174 offset:53248
	s_waitcnt lgkmcnt(0)
	v_mfma_f32_16x16x32_bf16 v[50:53], v[58:61], v[8:11], v[50:53]
	ds_read_b128 v[58:61], v175 offset:53248
	s_waitcnt lgkmcnt(0)
	v_mfma_f32_16x16x32_bf16 v[50:53], v[58:61], v[12:15], v[50:53]
	v_mul_f32_e64 v58, v54, s20
	v_mul_f32_e64 v59, v55, s20
	s_nop 5
	v_pk_add_f32 v[50:51], v[42:43], v[50:51] op_sel_hi:[0,1]
	v_pk_mul_f32 v[58:59], v[58:59], v[54:55]
	v_pk_add_f32 v[52:53], v[42:43], v[52:53] op_sel_hi:[0,1]
	v_pk_fma_f32 v[58:59], v[58:59], v[54:55], v[54:55]
	v_pk_mul_f32 v[54:55], v[54:55], 0.5 op_sel_hi:[1,0]
	v_pk_mul_f32 v[58:59], v[58:59], s[22:23] op_sel_hi:[1,0]
	s_nop 0
	v_mul_f32_e64 v48, |v58|, -2.0
	v_mul_f32_e32 v48, 0x3fb8aa3b, v48
	v_exp_f32_e32 v60, v48
	v_cmp_gt_f32_e32 vcc, 0, v58
	v_cmp_gt_f32_e64 s[4:5], 0, v59
	v_add_f32_e32 v48, 1.0, v60
	v_rcp_f32_e32 v62, v48
	v_mul_f32_e64 v48, |v59|, -2.0
	v_mul_f32_e32 v48, 0x3fb8aa3b, v48
	v_exp_f32_e32 v61, v48
	s_nop 0
	v_add_f32_e32 v48, 1.0, v61
	v_rcp_f32_e32 v63, v48
	v_pk_add_f32 v[104:105], v[60:61], 1.0 op_sel_hi:[1,0] neg_lo:[1,0] neg_hi:[1,0]
	v_lshlrev_b32_e32 v48, 16, v49
	v_and_b32_e32 v49, 0xffff0000, v49
	v_pk_mul_f32 v[60:61], v[104:105], v[62:63]
	s_nop 0
	v_cndmask_b32_e64 v59, v61, -v61, s[4:5]
	v_cndmask_b32_e64 v58, v60, -v60, vcc
	v_pk_add_f32 v[58:59], v[58:59], 1.0 op_sel_hi:[1,0]
	s_nop 0
	v_pk_mul_f32 v[54:55], v[54:55], v[58:59]
	s_nop 0
	v_pk_mul_f32 v[50:51], v[54:55], v[50:51]
	v_pk_mul_f32 v[54:55], v[48:49], s[20:21] op_sel_hi:[1,0]
	v_cvt_pk_bf16_f32 v50, v50, v51
	v_pk_mul_f32 v[54:55], v[54:55], v[48:49]
	s_nop 0
	v_pk_fma_f32 v[54:55], v[54:55], v[48:49], v[48:49]
	v_pk_mul_f32 v[48:49], v[48:49], 0.5 op_sel_hi:[1,0]
	v_pk_mul_f32 v[54:55], v[54:55], s[22:23] op_sel_hi:[1,0]
	s_nop 0
	v_mul_f32_e64 v58, |v54|, -2.0
	v_mul_f32_e32 v58, 0x3fb8aa3b, v58
	v_exp_f32_e32 v58, v58
	v_cmp_gt_f32_e32 vcc, 0, v54
	v_cmp_gt_f32_e64 s[4:5], 0, v55
	v_add_f32_e32 v59, 1.0, v58
	v_rcp_f32_e32 v60, v59
	v_mul_f32_e64 v59, |v55|, -2.0
	v_mul_f32_e32 v59, 0x3fb8aa3b, v59
	v_exp_f32_e32 v59, v59
	s_nop 0
	v_pk_add_f32 v[62:63], v[58:59], 1.0 op_sel_hi:[1,0] neg_lo:[1,0] neg_hi:[1,0]
	v_add_f32_e32 v58, 1.0, v59
	v_rcp_f32_e32 v61, v58
	s_nop 0
	v_pk_mul_f32 v[58:59], v[62:63], v[60:61]
	s_nop 0
	v_cndmask_b32_e64 v55, v59, -v59, s[4:5]
	v_cndmask_b32_e64 v54, v58, -v58, vcc
	v_pk_add_f32 v[54:55], v[54:55], 1.0 op_sel_hi:[1,0]
	s_nop 0
	v_pk_mul_f32 v[48:49], v[48:49], v[54:55]
	s_nop 0
	v_pk_mul_f32 v[48:49], v[48:49], v[52:53]
	ds_read_b128 v[52:55], v177 offset:57344
	v_cvt_pk_bf16_f32 v51, v48, v49
	global_store_dwordx2 v[56:57], v[50:51], off offset:160
	ds_read_b128 v[48:51], v176 offset:57344
	s_waitcnt lgkmcnt(0)
	v_mfma_f32_16x16x32_bf16 v[48:51], v[48:51], v[0:3], 0
	v_mfma_f32_16x16x32_bf16 v[48:51], v[52:55], v[4:7], v[48:51]
	ds_read_b128 v[52:55], v178 offset:57344
	s_waitcnt lgkmcnt(0)
	v_mfma_f32_16x16x32_bf16 v[48:51], v[52:55], v[8:11], v[48:51]
	ds_read_b128 v[52:55], v179 offset:57344
	s_waitcnt lgkmcnt(0)
	v_mfma_f32_16x16x32_bf16 v[48:51], v[52:55], v[12:15], v[48:51]
	s_waitcnt vmcnt(7)
	v_lshlrev_b32_e32 v52, 16, v46
	v_and_b32_e32 v53, 0xffff0000, v46
	v_pk_mul_f32 v[54:55], v[52:53], s[20:21] op_sel_hi:[1,0]
	s_nop 3
	v_pk_add_f32 v[48:49], v[42:43], v[48:49] op_sel_hi:[0,1]
	v_pk_mul_f32 v[54:55], v[54:55], v[52:53]
	v_pk_add_f32 v[50:51], v[42:43], v[50:51] op_sel_hi:[0,1]
	v_pk_fma_f32 v[54:55], v[54:55], v[52:53], v[52:53]
	v_pk_mul_f32 v[52:53], v[52:53], 0.5 op_sel_hi:[1,0]
	v_pk_mul_f32 v[54:55], v[54:55], s[22:23] op_sel_hi:[1,0]
	s_nop 0
	v_mul_f32_e64 v46, |v54|, -2.0
	v_mul_f32_e32 v46, 0x3fb8aa3b, v46
	v_exp_f32_e32 v58, v46
	v_cmp_gt_f32_e32 vcc, 0, v54
	v_cmp_gt_f32_e64 s[4:5], 0, v55
	v_add_f32_e32 v46, 1.0, v58
	v_rcp_f32_e32 v60, v46
	v_mul_f32_e64 v46, |v55|, -2.0
	v_mul_f32_e32 v46, 0x3fb8aa3b, v46
	v_exp_f32_e32 v59, v46
	s_nop 0
	v_add_f32_e32 v46, 1.0, v59
	v_rcp_f32_e32 v61, v46
	v_pk_add_f32 v[62:63], v[58:59], 1.0 op_sel_hi:[1,0] neg_lo:[1,0] neg_hi:[1,0]
	v_lshlrev_b32_e32 v46, 16, v47
	v_and_b32_e32 v47, 0xffff0000, v47
	v_pk_mul_f32 v[58:59], v[62:63], v[60:61]
	s_nop 0
	v_cndmask_b32_e64 v55, v59, -v59, s[4:5]
	v_cndmask_b32_e64 v54, v58, -v58, vcc
	v_pk_add_f32 v[54:55], v[54:55], 1.0 op_sel_hi:[1,0]
	s_nop 0
	v_pk_mul_f32 v[52:53], v[52:53], v[54:55]
	s_nop 0
	v_pk_mul_f32 v[48:49], v[52:53], v[48:49]
	v_pk_mul_f32 v[52:53], v[46:47], s[20:21] op_sel_hi:[1,0]
	v_cvt_pk_bf16_f32 v48, v48, v49
	v_pk_mul_f32 v[52:53], v[52:53], v[46:47]
	s_nop 0
	v_pk_fma_f32 v[52:53], v[52:53], v[46:47], v[46:47]
	v_pk_mul_f32 v[46:47], v[46:47], 0.5 op_sel_hi:[1,0]
	v_pk_mul_f32 v[52:53], v[52:53], s[22:23] op_sel_hi:[1,0]
	s_nop 0
	v_mul_f32_e64 v54, |v52|, -2.0
	v_mul_f32_e32 v54, 0x3fb8aa3b, v54
	v_exp_f32_e32 v54, v54
	v_cmp_gt_f32_e32 vcc, 0, v52
	v_cmp_gt_f32_e64 s[4:5], 0, v53
	v_add_f32_e32 v55, 1.0, v54
	v_rcp_f32_e32 v58, v55
	v_mul_f32_e64 v55, |v53|, -2.0
	v_mul_f32_e32 v55, 0x3fb8aa3b, v55
	v_exp_f32_e32 v55, v55
	s_nop 0
	v_pk_add_f32 v[60:61], v[54:55], 1.0 op_sel_hi:[1,0] neg_lo:[1,0] neg_hi:[1,0]
	v_add_f32_e32 v54, 1.0, v55
	v_rcp_f32_e32 v59, v54
	s_nop 0
	v_pk_mul_f32 v[54:55], v[60:61], v[58:59]
	s_nop 0
	v_cndmask_b32_e64 v53, v55, -v55, s[4:5]
	v_cndmask_b32_e64 v52, v54, -v54, vcc
	v_pk_add_f32 v[52:53], v[52:53], 1.0 op_sel_hi:[1,0]
	s_nop 0
	v_pk_mul_f32 v[46:47], v[46:47], v[52:53]
	s_nop 0
	v_pk_mul_f32 v[46:47], v[46:47], v[50:51]
	s_nop 0
	v_cvt_pk_bf16_f32 v49, v46, v47
	global_store_dwordx2 v[56:57], v[48:49], off offset:192
	ds_read_b128 v[46:49], v180 offset:61440
	s_waitcnt lgkmcnt(0)
	v_mfma_f32_16x16x32_bf16 v[0:3], v[46:49], v[0:3], 0
	ds_read_b128 v[46:49], v181 offset:61440
	s_waitcnt lgkmcnt(0)
	v_mfma_f32_16x16x32_bf16 v[0:3], v[46:49], v[4:7], v[0:3]
	ds_read_b128 v[4:7], v182 offset:61440
	s_waitcnt lgkmcnt(0)
	v_mfma_f32_16x16x32_bf16 v[0:3], v[4:7], v[8:11], v[0:3]
	ds_read_b128 v[4:7], v183 offset:61440
	s_waitcnt lgkmcnt(0)
	v_mfma_f32_16x16x32_bf16 v[0:3], v[4:7], v[12:15], v[0:3]
	s_waitcnt vmcnt(7)
	v_lshlrev_b32_e32 v4, 16, v44
	v_and_b32_e32 v5, 0xffff0000, v44
	v_pk_mul_f32 v[6:7], v[4:5], s[20:21] op_sel_hi:[1,0]
	s_nop 3
	v_pk_add_f32 v[0:1], v[42:43], v[0:1] op_sel_hi:[0,1]
	v_pk_mul_f32 v[6:7], v[6:7], v[4:5]
	v_pk_add_f32 v[2:3], v[42:43], v[2:3] op_sel_hi:[0,1]
	v_pk_fma_f32 v[6:7], v[6:7], v[4:5], v[4:5]
	v_pk_mul_f32 v[4:5], v[4:5], 0.5 op_sel_hi:[1,0]
	v_pk_mul_f32 v[6:7], v[6:7], s[22:23] op_sel_hi:[1,0]
	s_nop 0
	v_mul_f32_e64 v8, |v6|, -2.0
	v_mul_f32_e32 v8, 0x3fb8aa3b, v8
	v_exp_f32_e32 v8, v8
	v_cmp_gt_f32_e32 vcc, 0, v6
	v_cmp_gt_f32_e64 s[4:5], 0, v7
	v_add_f32_e32 v9, 1.0, v8
	v_rcp_f32_e32 v10, v9
	v_mul_f32_e64 v9, |v7|, -2.0
	v_mul_f32_e32 v9, 0x3fb8aa3b, v9
	v_exp_f32_e32 v9, v9
	s_nop 0
	v_pk_add_f32 v[12:13], v[8:9], 1.0 op_sel_hi:[1,0] neg_lo:[1,0] neg_hi:[1,0]
	v_add_f32_e32 v8, 1.0, v9
	v_rcp_f32_e32 v11, v8
	s_nop 0
	v_pk_mul_f32 v[8:9], v[12:13], v[10:11]
	s_nop 0
	v_cndmask_b32_e64 v7, v9, -v9, s[4:5]
	v_cndmask_b32_e64 v6, v8, -v8, vcc
	v_pk_add_f32 v[6:7], v[6:7], 1.0 op_sel_hi:[1,0]
	s_nop 0
	v_pk_mul_f32 v[4:5], v[4:5], v[6:7]
	s_nop 0
	v_pk_mul_f32 v[0:1], v[4:5], v[0:1]
	v_lshlrev_b32_e32 v4, 16, v45
	v_and_b32_e32 v5, 0xffff0000, v45
	v_pk_mul_f32 v[6:7], v[4:5], s[20:21] op_sel_hi:[1,0]
	v_cvt_pk_bf16_f32 v0, v0, v1
	v_pk_mul_f32 v[6:7], v[6:7], v[4:5]
	s_nop 0
	v_pk_fma_f32 v[6:7], v[6:7], v[4:5], v[4:5]
	v_pk_mul_f32 v[4:5], v[4:5], 0.5 op_sel_hi:[1,0]
	v_pk_mul_f32 v[6:7], v[6:7], s[22:23] op_sel_hi:[1,0]
	s_nop 0
	v_mul_f32_e64 v8, |v6|, -2.0
	v_mul_f32_e32 v8, 0x3fb8aa3b, v8
	v_exp_f32_e32 v8, v8
	v_cmp_gt_f32_e32 vcc, 0, v6
	v_cmp_gt_f32_e64 s[4:5], 0, v7
	v_add_f32_e32 v9, 1.0, v8
	v_rcp_f32_e32 v10, v9
	v_mul_f32_e64 v9, |v7|, -2.0
	v_mul_f32_e32 v9, 0x3fb8aa3b, v9
	v_exp_f32_e32 v9, v9
	s_nop 0
	v_pk_add_f32 v[12:13], v[8:9], 1.0 op_sel_hi:[1,0] neg_lo:[1,0] neg_hi:[1,0]
	v_add_f32_e32 v8, 1.0, v9
	v_rcp_f32_e32 v11, v8
	s_nop 0
	v_pk_mul_f32 v[8:9], v[12:13], v[10:11]
	s_nop 0
	v_cndmask_b32_e64 v7, v9, -v9, s[4:5]
	v_cndmask_b32_e64 v6, v8, -v8, vcc
	v_pk_add_f32 v[6:7], v[6:7], 1.0 op_sel_hi:[1,0]
	s_nop 0
	v_pk_mul_f32 v[4:5], v[4:5], v[6:7]
	s_nop 0
	v_pk_mul_f32 v[2:3], v[4:5], v[2:3]
	s_nop 0
	v_cvt_pk_bf16_f32 v1, v2, v3
	global_store_dwordx2 v[56:57], v[0:1], off offset:224
	s_cbranch_scc1 .LBB0_360

.Lcvt_join:
	s_mov_b64 exec, s[18:19]
	s_mov_b64 s[4:5], exec
	s_waitcnt vmcnt(0)
	ds_write_b32 v4, v21
	ds_write_b32 v5, v22
	ds_write_b32 v7, v23
	ds_write_b32 v9, v24
	ds_write_b32 v11, v25
	ds_write_b32 v13, v26
	ds_write_b32 v15, v27
	s_branch .LBB0_438
	s_nop 0
	s_nop 0
	s_nop 0
	s_nop 0
	s_nop 0
	s_nop 0
	s_nop 0
	s_nop 0
.LBB0_486:
	s_mov_b64 s[6:7], 0x600000
	s_movk_i32 s23, 0x1600
	s_mov_b64 s[8:9], 0x1600
	s_cbranch_execz .LBB0_464
	s_branch .LBB0_465
